# attn0 compute interleaved: row max of tile t-1 under QK MFMAs of tile t, each tile's PV MFMAs issued right after its exp/pack
# speedup vs baseline: 1.0050x; 1.0050x over previous
.La0_have1:
	v_cndmask_b32_e64 v160, v160, v239, s[6:7]
	v_cndmask_b32_e64 v161, v161, v239, s[38:39]
	v_cndmask_b32_e64 v162, v162, v239, s[40:41]
	v_cndmask_b32_e64 v163, v163, v239, s[42:43]
	v_cndmask_b32_e64 v164, v164, v239, s[44:45]
	v_cndmask_b32_e64 v165, v165, v239, s[46:47]
	v_cndmask_b32_e64 v166, v166, v239, s[48:49]
	v_cndmask_b32_e64 v167, v167, v239, s[50:51]
	v_cndmask_b32_e64 v168, v168, v239, s[52:53]
	v_cndmask_b32_e64 v169, v169, v239, s[54:55]
	v_cndmask_b32_e64 v170, v170, v239, s[56:57]
	v_cndmask_b32_e64 v171, v171, v239, s[58:59]
	v_cndmask_b32_e64 v172, v172, v239, s[60:61]
	v_cndmask_b32_e64 v173, v173, v239, s[62:63]
	v_cndmask_b32_e64 v174, v174, v239, s[64:65]
	v_cndmask_b32_e64 v175, v175, v239, s[66:67]
	v_max3_f32 v12, v160, v161, v162
	v_max3_f32 v13, v163, v164, v165
	v_max3_f32 v14, v166, v167, v168
	v_max3_f32 v15, v169, v170, v171
	v_max3_f32 v12, v12, v172, v173
	v_max3_f32 v13, v13, v174, v175
	s_cmp_lt_i32 s85, 2
	s_cbranch_scc1 .La0_miss2
	s_add_i32 s68, s72, 14
	s_and_b32 s68, s68, 15
	s_lshl_b32 s68, s68, 13
	v_add_u32_e32 v158, s68, v152
	ds_read_b128 v[48:51], v158
	ds_read_b128 v[52:55], v158 offset:1024
	ds_read_b128 v[56:59], v158 offset:2048
	ds_read_b128 v[60:63], v158 offset:3072
	s_waitcnt lgkmcnt(3)
	v_mfma_f32_32x32x16_bf16 v[192:207], v[48:51], v[92:95], 0
	s_waitcnt lgkmcnt(2)
	v_mfma_f32_32x32x16_bf16 v[192:207], v[52:55], v[88:91], v[192:207]
	s_waitcnt lgkmcnt(1)
	v_mfma_f32_32x32x16_bf16 v[192:207], v[56:59], v[84:87], v[192:207]
	s_waitcnt lgkmcnt(0)
	v_mfma_f32_32x32x16_bf16 v[192:207], v[60:63], v[80:83], v[192:207]
	s_branch .La0_have2

.La0_have2:
	v_max3_f32 v14, v14, v176, v177
	v_max3_f32 v15, v15, v178, v179
	v_max3_f32 v12, v12, v180, v181
	v_max3_f32 v13, v13, v182, v183
	v_max3_f32 v14, v14, v184, v185
	v_max3_f32 v15, v15, v186, v187
	v_max3_f32 v12, v12, v188, v189
	v_max3_f32 v13, v13, v190, v191
	s_cmp_lt_i32 s85, 1
	s_cbranch_scc1 .La0_miss3
	s_add_i32 s68, s72, 15
	s_and_b32 s68, s68, 15
	s_lshl_b32 s68, s68, 13
	v_add_u32_e32 v158, s68, v152
	ds_read_b128 v[224:227], v158
	ds_read_b128 v[228:231], v158 offset:1024
	ds_read_b128 v[2:5], v158 offset:2048
	ds_read_b128 v[8:11], v158 offset:3072
	s_waitcnt lgkmcnt(3)
	v_mfma_f32_32x32x16_bf16 v[208:223], v[224:227], v[92:95], 0
	s_waitcnt lgkmcnt(2)
	v_mfma_f32_32x32x16_bf16 v[208:223], v[228:231], v[88:91], v[208:223]
	s_waitcnt lgkmcnt(1)
	v_mfma_f32_32x32x16_bf16 v[208:223], v[2:5], v[84:87], v[208:223]
	s_waitcnt lgkmcnt(0)
	v_mfma_f32_32x32x16_bf16 v[208:223], v[8:11], v[80:83], v[208:223]
	s_branch .La0_have3

.La0_have3:
	v_max3_f32 v14, v14, v192, v193
	v_max3_f32 v15, v15, v194, v195
	v_max3_f32 v12, v12, v196, v197
	v_max3_f32 v13, v13, v198, v199
	v_max3_f32 v14, v14, v200, v201
	v_max3_f32 v15, v15, v202, v203
	v_max3_f32 v12, v12, v204, v205
	v_max3_f32 v13, v13, v206, v207
	s_add_i32 s68, s72, 16
	s_and_b32 s68, s68, 15
	s_lshl_b32 s68, s68, 13
	v_add_u32_e32 v158, s68, v152
	ds_read_b128 v[48:51], v158
	ds_read_b128 v[52:55], v158 offset:1024
	ds_read_b128 v[56:59], v158 offset:2048
	ds_read_b128 v[60:63], v158 offset:3072
	s_waitcnt lgkmcnt(3)
	v_mfma_f32_32x32x16_bf16 v[96:111], v[48:51], v[92:95], 0
	s_waitcnt lgkmcnt(2)
	v_mfma_f32_32x32x16_bf16 v[96:111], v[52:55], v[88:91], v[96:111]
	s_waitcnt lgkmcnt(1)
	v_mfma_f32_32x32x16_bf16 v[96:111], v[56:59], v[84:87], v[96:111]
	s_waitcnt lgkmcnt(0)
	v_mfma_f32_32x32x16_bf16 v[96:111], v[60:63], v[80:83], v[96:111]
	v_max3_f32 v14, v14, v208, v209
	v_max3_f32 v15, v15, v210, v211
	v_max3_f32 v12, v12, v212, v213
	v_max3_f32 v13, v13, v214, v215
	v_max3_f32 v14, v14, v216, v217
	v_max3_f32 v15, v15, v218, v219
	v_max3_f32 v12, v12, v220, v221
	v_max3_f32 v13, v13, v222, v223
	s_nop 7
	s_nop 4
	v_cndmask_b32_e64 v96, v96, v239, s[4:5]
	v_cndmask_b32_e64 v97, v239, v97, s[6:7]
	v_cndmask_b32_e64 v98, v98, v239, s[8:9]
	v_cndmask_b32_e64 v99, v99, v239, s[10:11]
	v_cndmask_b32_e64 v100, v100, v239, s[12:13]
	v_cndmask_b32_e64 v101, v101, v239, s[14:15]
	v_cndmask_b32_e64 v102, v102, v239, s[16:17]
	v_cndmask_b32_e64 v103, v103, v239, s[18:19]
	v_cndmask_b32_e64 v104, v104, v239, s[20:21]
	v_cndmask_b32_e64 v105, v105, v239, s[22:23]
	v_cndmask_b32_e64 v106, v106, v239, s[24:25]
	v_cndmask_b32_e64 v107, v107, v239, s[26:27]
	v_cndmask_b32_e64 v108, v108, v239, s[28:29]
	v_cndmask_b32_e64 v109, v109, v239, s[30:31]
	v_cndmask_b32_e64 v110, v110, v239, s[34:35]
	v_cndmask_b32_e64 v111, v111, v239, s[36:37]
	v_max3_f32 v14, v14, v96, v97
	v_max3_f32 v15, v15, v98, v99
	v_max3_f32 v12, v12, v100, v101
	v_max3_f32 v13, v13, v102, v103
	v_max3_f32 v14, v14, v104, v105
	v_max3_f32 v15, v15, v106, v107
	v_max3_f32 v12, v12, v108, v109
	v_max3_f32 v13, v13, v110, v111
	v_max3_f32 v12, v12, v13, v14
	v_max_f32_e32 v12, v12, v15
	ds_bpermute_b32 v13, v157, v12
	s_waitcnt lgkmcnt(0)
	v_max_f32_e32 v1, v12, v13
	s_add_i32 s68, s72, 16
	s_and_b32 s68, s68, 15
	s_lshl_b32 s68, s68, 13
	v_add_u32_e32 v158, s68, v152
	ds_read_b128 v[48:51], v158 offset:4096
	ds_read_b128 v[52:55], v158 offset:5120
	ds_read_b128 v[56:59], v158 offset:6144
	ds_read_b128 v[60:63], v158 offset:7168
	v_sub_f32_e32 v96, v96, v1
	v_sub_f32_e32 v97, v97, v1
	v_sub_f32_e32 v98, v98, v1
	v_sub_f32_e32 v99, v99, v1
	v_sub_f32_e32 v100, v100, v1
	v_sub_f32_e32 v101, v101, v1
	v_sub_f32_e32 v102, v102, v1
	v_sub_f32_e32 v103, v103, v1
	v_sub_f32_e32 v104, v104, v1
	v_sub_f32_e32 v105, v105, v1
	v_sub_f32_e32 v106, v106, v1
	v_sub_f32_e32 v107, v107, v1
	v_sub_f32_e32 v108, v108, v1
	v_sub_f32_e32 v109, v109, v1
	v_sub_f32_e32 v110, v110, v1
	v_sub_f32_e32 v111, v111, v1
	v_exp_f32_e32 v96, v96
	v_exp_f32_e32 v97, v97
	v_exp_f32_e32 v98, v98
	v_exp_f32_e32 v99, v99
	v_exp_f32_e32 v100, v100
	v_exp_f32_e32 v101, v101
	v_exp_f32_e32 v102, v102
	v_exp_f32_e32 v103, v103
	v_exp_f32_e32 v104, v104
	v_exp_f32_e32 v105, v105
	v_exp_f32_e32 v106, v106
	v_exp_f32_e32 v107, v107
	v_exp_f32_e32 v108, v108
	v_exp_f32_e32 v109, v109
	v_exp_f32_e32 v110, v110
	v_exp_f32_e32 v111, v111
	v_add_f32_e32 v12, v96, v97
	v_add_f32_e32 v13, v98, v99
	v_add_f32_e32 v14, v100, v101
	v_add_f32_e32 v15, v102, v103
	v_add_f32_e32 v12, v104, v12
	v_add_f32_e32 v13, v105, v13
	v_add_f32_e32 v14, v106, v14
	v_add_f32_e32 v15, v107, v15
	v_add_f32_e32 v12, v108, v12
	v_add_f32_e32 v13, v109, v13
	v_add_f32_e32 v14, v110, v14
	v_add_f32_e32 v15, v111, v15
	v_cvt_pk_bf16_f32 v96, v96, v97
	v_cvt_pk_bf16_f32 v97, v98, v99
	v_cvt_pk_bf16_f32 v98, v100, v101
	v_cvt_pk_bf16_f32 v99, v102, v103
	v_cvt_pk_bf16_f32 v100, v104, v105
	v_cvt_pk_bf16_f32 v101, v106, v107
	v_cvt_pk_bf16_f32 v102, v108, v109
	v_cvt_pk_bf16_f32 v103, v110, v111
	s_nop 1
	s_waitcnt lgkmcnt(3)
	v_mfma_f32_32x32x16_bf16 v[32:47], v[48:51], v[96:99], 0
	s_waitcnt lgkmcnt(1)
	v_mfma_f32_32x32x16_bf16 v[16:31], v[56:59], v[96:99], 0
	v_mfma_f32_32x32x16_bf16 v[32:47], v[52:55], v[100:103], v[32:47]
	s_waitcnt lgkmcnt(0)
	v_mfma_f32_32x32x16_bf16 v[16:31], v[60:63], v[100:103], v[16:31]
	s_cmp_lt_i32 s85, 4
	s_cbranch_scc1 .La0_pvskip0
	s_add_i32 s68, s72, 12
	s_and_b32 s68, s68, 15
	s_lshl_b32 s68, s68, 13
	v_add_u32_e32 v158, s68, v152
	ds_read_b128 v[224:227], v158 offset:4096
	ds_read_b128 v[228:231], v158 offset:5120
	ds_read_b128 v[2:5], v158 offset:6144
	ds_read_b128 v[8:11], v158 offset:7168
	v_sub_f32_e32 v160, v160, v1
	v_sub_f32_e32 v161, v161, v1
	v_sub_f32_e32 v162, v162, v1
	v_sub_f32_e32 v163, v163, v1
	v_sub_f32_e32 v164, v164, v1
	v_sub_f32_e32 v165, v165, v1
	v_sub_f32_e32 v166, v166, v1
	v_sub_f32_e32 v167, v167, v1
	v_sub_f32_e32 v168, v168, v1
	v_sub_f32_e32 v169, v169, v1
	v_sub_f32_e32 v170, v170, v1
	v_sub_f32_e32 v171, v171, v1
	v_sub_f32_e32 v172, v172, v1
	v_sub_f32_e32 v173, v173, v1
	v_sub_f32_e32 v174, v174, v1
	v_sub_f32_e32 v175, v175, v1
	v_exp_f32_e32 v160, v160
	v_exp_f32_e32 v161, v161
	v_exp_f32_e32 v162, v162
	v_exp_f32_e32 v163, v163
	v_exp_f32_e32 v164, v164
	v_exp_f32_e32 v165, v165
	v_exp_f32_e32 v166, v166
	v_exp_f32_e32 v167, v167
	v_exp_f32_e32 v168, v168
	v_exp_f32_e32 v169, v169
	v_exp_f32_e32 v170, v170
	v_exp_f32_e32 v171, v171
	v_exp_f32_e32 v172, v172
	v_exp_f32_e32 v173, v173
	v_exp_f32_e32 v174, v174
	v_exp_f32_e32 v175, v175
	v_add_f32_e32 v12, v160, v12
	v_add_f32_e32 v13, v161, v13
	v_add_f32_e32 v14, v162, v14
	v_add_f32_e32 v15, v163, v15
	v_add_f32_e32 v12, v164, v12
	v_add_f32_e32 v13, v165, v13
	v_add_f32_e32 v14, v166, v14
	v_add_f32_e32 v15, v167, v15
	v_add_f32_e32 v12, v168, v12
	v_add_f32_e32 v13, v169, v13
	v_add_f32_e32 v14, v170, v14
	v_add_f32_e32 v15, v171, v15
	v_add_f32_e32 v12, v172, v12
	v_add_f32_e32 v13, v173, v13
	v_add_f32_e32 v14, v174, v14
	v_add_f32_e32 v15, v175, v15
	v_cvt_pk_bf16_f32 v160, v160, v161
	v_cvt_pk_bf16_f32 v161, v162, v163
	v_cvt_pk_bf16_f32 v162, v164, v165
	v_cvt_pk_bf16_f32 v163, v166, v167
	v_cvt_pk_bf16_f32 v164, v168, v169
	v_cvt_pk_bf16_f32 v165, v170, v171
	v_cvt_pk_bf16_f32 v166, v172, v173
	v_cvt_pk_bf16_f32 v167, v174, v175
	s_nop 1
	s_waitcnt lgkmcnt(3)
	v_mfma_f32_32x32x16_bf16 v[32:47], v[224:227], v[160:163], v[32:47]
	s_waitcnt lgkmcnt(1)
	v_mfma_f32_32x32x16_bf16 v[16:31], v[2:5], v[160:163], v[16:31]
	v_mfma_f32_32x32x16_bf16 v[32:47], v[228:231], v[164:167], v[32:47]
	s_waitcnt lgkmcnt(0)
	v_mfma_f32_32x32x16_bf16 v[16:31], v[8:11], v[164:167], v[16:31]
.La0_pvskip0:
	s_cmp_lt_i32 s85, 3
	s_cbranch_scc1 .La0_pvskip1
	s_add_i32 s68, s72, 13
	s_and_b32 s68, s68, 15
	s_lshl_b32 s68, s68, 13
	v_add_u32_e32 v158, s68, v152
	ds_read_b128 v[48:51], v158 offset:4096
	ds_read_b128 v[52:55], v158 offset:5120
	ds_read_b128 v[56:59], v158 offset:6144
	ds_read_b128 v[60:63], v158 offset:7168
	v_sub_f32_e32 v176, v176, v1
	v_sub_f32_e32 v177, v177, v1
	v_sub_f32_e32 v178, v178, v1
	v_sub_f32_e32 v179, v179, v1
	v_sub_f32_e32 v180, v180, v1
	v_sub_f32_e32 v181, v181, v1
	v_sub_f32_e32 v182, v182, v1
	v_sub_f32_e32 v183, v183, v1
	v_sub_f32_e32 v184, v184, v1
	v_sub_f32_e32 v185, v185, v1
	v_sub_f32_e32 v186, v186, v1
	v_sub_f32_e32 v187, v187, v1
	v_sub_f32_e32 v188, v188, v1
	v_sub_f32_e32 v189, v189, v1
	v_sub_f32_e32 v190, v190, v1
	v_sub_f32_e32 v191, v191, v1
	v_exp_f32_e32 v176, v176
	v_exp_f32_e32 v177, v177
	v_exp_f32_e32 v178, v178
	v_exp_f32_e32 v179, v179
	v_exp_f32_e32 v180, v180
	v_exp_f32_e32 v181, v181
	v_exp_f32_e32 v182, v182
	v_exp_f32_e32 v183, v183
	v_exp_f32_e32 v184, v184
	v_exp_f32_e32 v185, v185
	v_exp_f32_e32 v186, v186
	v_exp_f32_e32 v187, v187
	v_exp_f32_e32 v188, v188
	v_exp_f32_e32 v189, v189
	v_exp_f32_e32 v190, v190
	v_exp_f32_e32 v191, v191
	v_add_f32_e32 v12, v176, v12
	v_add_f32_e32 v13, v177, v13
	v_add_f32_e32 v14, v178, v14
	v_add_f32_e32 v15, v179, v15
	v_add_f32_e32 v12, v180, v12
	v_add_f32_e32 v13, v181, v13
	v_add_f32_e32 v14, v182, v14
	v_add_f32_e32 v15, v183, v15
	v_add_f32_e32 v12, v184, v12
	v_add_f32_e32 v13, v185, v13
	v_add_f32_e32 v14, v186, v14
	v_add_f32_e32 v15, v187, v15
	v_add_f32_e32 v12, v188, v12
	v_add_f32_e32 v13, v189, v13
	v_add_f32_e32 v14, v190, v14
	v_add_f32_e32 v15, v191, v15
	v_cvt_pk_bf16_f32 v176, v176, v177
	v_cvt_pk_bf16_f32 v177, v178, v179
	v_cvt_pk_bf16_f32 v178, v180, v181
	v_cvt_pk_bf16_f32 v179, v182, v183
	v_cvt_pk_bf16_f32 v180, v184, v185
	v_cvt_pk_bf16_f32 v181, v186, v187
	v_cvt_pk_bf16_f32 v182, v188, v189
	v_cvt_pk_bf16_f32 v183, v190, v191
	s_nop 1
	s_waitcnt lgkmcnt(3)
	v_mfma_f32_32x32x16_bf16 v[32:47], v[48:51], v[176:179], v[32:47]
	s_waitcnt lgkmcnt(1)
	v_mfma_f32_32x32x16_bf16 v[16:31], v[56:59], v[176:179], v[16:31]
	v_mfma_f32_32x32x16_bf16 v[32:47], v[52:55], v[180:183], v[32:47]
	s_waitcnt lgkmcnt(0)
	v_mfma_f32_32x32x16_bf16 v[16:31], v[60:63], v[180:183], v[16:31]
.La0_pvskip1:
	s_cmp_lt_i32 s85, 2
	s_cbranch_scc1 .La0_pvskip2
	s_add_i32 s68, s72, 14
	s_and_b32 s68, s68, 15
	s_lshl_b32 s68, s68, 13
	v_add_u32_e32 v158, s68, v152
	ds_read_b128 v[224:227], v158 offset:4096
	ds_read_b128 v[228:231], v158 offset:5120
	ds_read_b128 v[2:5], v158 offset:6144
	ds_read_b128 v[8:11], v158 offset:7168
	v_sub_f32_e32 v192, v192, v1
	v_sub_f32_e32 v193, v193, v1
	v_sub_f32_e32 v194, v194, v1
	v_sub_f32_e32 v195, v195, v1
	v_sub_f32_e32 v196, v196, v1
	v_sub_f32_e32 v197, v197, v1
	v_sub_f32_e32 v198, v198, v1
	v_sub_f32_e32 v199, v199, v1
	v_sub_f32_e32 v200, v200, v1
	v_sub_f32_e32 v201, v201, v1
	v_sub_f32_e32 v202, v202, v1
	v_sub_f32_e32 v203, v203, v1
	v_sub_f32_e32 v204, v204, v1
	v_sub_f32_e32 v205, v205, v1
	v_sub_f32_e32 v206, v206, v1
	v_sub_f32_e32 v207, v207, v1
	v_exp_f32_e32 v192, v192
	v_exp_f32_e32 v193, v193
	v_exp_f32_e32 v194, v194
	v_exp_f32_e32 v195, v195
	v_exp_f32_e32 v196, v196
	v_exp_f32_e32 v197, v197
	v_exp_f32_e32 v198, v198
	v_exp_f32_e32 v199, v199
	v_exp_f32_e32 v200, v200
	v_exp_f32_e32 v201, v201
	v_exp_f32_e32 v202, v202
	v_exp_f32_e32 v203, v203
	v_exp_f32_e32 v204, v204
	v_exp_f32_e32 v205, v205
	v_exp_f32_e32 v206, v206
	v_exp_f32_e32 v207, v207
	v_add_f32_e32 v12, v192, v12
	v_add_f32_e32 v13, v193, v13
	v_add_f32_e32 v14, v194, v14
	v_add_f32_e32 v15, v195, v15
	v_add_f32_e32 v12, v196, v12
	v_add_f32_e32 v13, v197, v13
	v_add_f32_e32 v14, v198, v14
	v_add_f32_e32 v15, v199, v15
	v_add_f32_e32 v12, v200, v12
	v_add_f32_e32 v13, v201, v13
	v_add_f32_e32 v14, v202, v14
	v_add_f32_e32 v15, v203, v15
	v_add_f32_e32 v12, v204, v12
	v_add_f32_e32 v13, v205, v13
	v_add_f32_e32 v14, v206, v14
	v_add_f32_e32 v15, v207, v15
	v_cvt_pk_bf16_f32 v192, v192, v193
	v_cvt_pk_bf16_f32 v193, v194, v195
	v_cvt_pk_bf16_f32 v194, v196, v197
	v_cvt_pk_bf16_f32 v195, v198, v199
	v_cvt_pk_bf16_f32 v196, v200, v201
	v_cvt_pk_bf16_f32 v197, v202, v203
	v_cvt_pk_bf16_f32 v198, v204, v205
	v_cvt_pk_bf16_f32 v199, v206, v207
	s_nop 1
	s_waitcnt lgkmcnt(3)
	v_mfma_f32_32x32x16_bf16 v[32:47], v[224:227], v[192:195], v[32:47]
	s_waitcnt lgkmcnt(1)
	v_mfma_f32_32x32x16_bf16 v[16:31], v[2:5], v[192:195], v[16:31]
	v_mfma_f32_32x32x16_bf16 v[32:47], v[228:231], v[196:199], v[32:47]
	s_waitcnt lgkmcnt(0)
	v_mfma_f32_32x32x16_bf16 v[16:31], v[8:11], v[196:199], v[16:31]
.La0_pvskip2:
	s_cmp_lt_i32 s85, 1
	s_cbranch_scc1 .La0_pvskip3
	s_add_i32 s68, s72, 15
	s_and_b32 s68, s68, 15
	s_lshl_b32 s68, s68, 13
	v_add_u32_e32 v158, s68, v152
	ds_read_b128 v[48:51], v158 offset:4096
	ds_read_b128 v[52:55], v158 offset:5120
	ds_read_b128 v[56:59], v158 offset:6144
	ds_read_b128 v[60:63], v158 offset:7168
	v_sub_f32_e32 v208, v208, v1
	v_sub_f32_e32 v209, v209, v1
	v_sub_f32_e32 v210, v210, v1
	v_sub_f32_e32 v211, v211, v1
	v_sub_f32_e32 v212, v212, v1
	v_sub_f32_e32 v213, v213, v1
	v_sub_f32_e32 v214, v214, v1
	v_sub_f32_e32 v215, v215, v1
	v_sub_f32_e32 v216, v216, v1
	v_sub_f32_e32 v217, v217, v1
	v_sub_f32_e32 v218, v218, v1
	v_sub_f32_e32 v219, v219, v1
	v_sub_f32_e32 v220, v220, v1
	v_sub_f32_e32 v221, v221, v1
	v_sub_f32_e32 v222, v222, v1
	v_sub_f32_e32 v223, v223, v1
	v_exp_f32_e32 v208, v208
	v_exp_f32_e32 v209, v209
	v_exp_f32_e32 v210, v210
	v_exp_f32_e32 v211, v211
	v_exp_f32_e32 v212, v212
	v_exp_f32_e32 v213, v213
	v_exp_f32_e32 v214, v214
	v_exp_f32_e32 v215, v215
	v_exp_f32_e32 v216, v216
	v_exp_f32_e32 v217, v217
	v_exp_f32_e32 v218, v218
	v_exp_f32_e32 v219, v219
	v_exp_f32_e32 v220, v220
	v_exp_f32_e32 v221, v221
	v_exp_f32_e32 v222, v222
	v_exp_f32_e32 v223, v223
	v_add_f32_e32 v12, v208, v12
	v_add_f32_e32 v13, v209, v13
	v_add_f32_e32 v14, v210, v14
	v_add_f32_e32 v15, v211, v15
	v_add_f32_e32 v12, v212, v12
	v_add_f32_e32 v13, v213, v13
	v_add_f32_e32 v14, v214, v14
	v_add_f32_e32 v15, v215, v15
	v_add_f32_e32 v12, v216, v12
	v_add_f32_e32 v13, v217, v13
	v_add_f32_e32 v14, v218, v14
	v_add_f32_e32 v15, v219, v15
	v_add_f32_e32 v12, v220, v12
	v_add_f32_e32 v13, v221, v13
	v_add_f32_e32 v14, v222, v14
	v_add_f32_e32 v15, v223, v15
	v_cvt_pk_bf16_f32 v208, v208, v209
	v_cvt_pk_bf16_f32 v209, v210, v211
	v_cvt_pk_bf16_f32 v210, v212, v213
	v_cvt_pk_bf16_f32 v211, v214, v215
	v_cvt_pk_bf16_f32 v212, v216, v217
	v_cvt_pk_bf16_f32 v213, v218, v219
	v_cvt_pk_bf16_f32 v214, v220, v221
	v_cvt_pk_bf16_f32 v215, v222, v223
	s_nop 1
	s_waitcnt lgkmcnt(3)
	v_mfma_f32_32x32x16_bf16 v[32:47], v[48:51], v[208:211], v[32:47]
	s_waitcnt lgkmcnt(1)
	v_mfma_f32_32x32x16_bf16 v[16:31], v[56:59], v[208:211], v[16:31]
	v_mfma_f32_32x32x16_bf16 v[32:47], v[52:55], v[212:215], v[32:47]
	s_waitcnt lgkmcnt(0)
	v_mfma_f32_32x32x16_bf16 v[16:31], v[60:63], v[212:215], v[16:31]
.La0_pvskip3:
	v_add_f32_e32 v12, v12, v13
	v_add_f32_e32 v14, v14, v15
	v_add_f32_e32 v6, v12, v14
	s_nop 7
	s_nop 4
